# row-pass loops (3 LN copies): next row's loads prefetched one iteration ahead into v[106:121]
# speedup vs baseline: 1.0207x; 1.0011x over previous
.LBB0_330:
	s_or_b64 exec, exec, s[0:1]
	v_readlane_b32 s0, v255, 19
	v_readlane_b32 s1, v255, 20
	s_and_b64 vcc, exec, s[0:1]
	s_waitcnt lgkmcnt(0)
	s_barrier
	s_cbranch_vccz .LBB0_342
	v_mov_b32_e32 v1, v222
	s_mov_b64 s[4:5], s[56:57]
	v_readfirstlane_b32 s0, v1
	s_ashr_i32 s0, s0, 6
	s_add_i32 s6, s0, s90
	s_cmp_ge_i32 s6, s40
	s_cbranch_scc1 .LBB0_343
	v_and_b32_e32 v1, 63, v1
	v_readlane_b32 s0, v254, 13
	v_readlane_b32 s2, v254, 17
	v_lshlrev_b32_e32 v2, 4, v1
	v_readlane_b32 s1, v254, 14
	v_readlane_b32 s3, v254, 18
	s_nop 3
	global_load_dwordx4 v[4:7], v2, s[0:1]
	global_load_dwordx4 v[8:11], v2, s[0:1] offset:1024
	global_load_dwordx4 v[12:15], v2, s[2:3]
	global_load_dwordx4 v[16:19], v2, s[2:3] offset:1024
	global_load_dwordx4 v[20:23], v2, s[0:1] offset:2048
	global_load_dwordx4 v[24:27], v2, s[0:1] offset:3072
	global_load_dwordx4 v[28:31], v2, s[2:3] offset:2048
	global_load_dwordx4 v[32:35], v2, s[2:3] offset:3072
	v_readlane_b32 s0, v254, 21
	v_mov_b32_e32 v3, v0
	v_readlane_b32 s1, v254, 22
	s_add_u32 s2, s4, 0x200000
	s_addc_u32 s12, s5, 0
	v_lshl_add_u64 v[86:87], s[0:1], 0, v[2:3]
	v_readlane_b32 s0, v254, 19
	v_readlane_b32 s1, v254, 20
	s_ashr_i32 s7, s6, 31
	v_lshlrev_b32_e32 v38, 2, v1
	v_lshl_add_u64 v[88:89], s[0:1], 0, v[2:3]
	v_and_b32_e32 v2, 64, v232
	v_add_u32_e32 v2, 64, v2
	v_xor_b32_e32 v3, 1, v232
	v_cmp_lt_i32_e32 vcc, v3, v2
	v_readlane_b32 s0, v253, 54
	v_readlane_b32 s1, v253, 55
	v_cndmask_b32_e32 v3, v232, v3, vcc
	v_lshlrev_b32_e32 v97, 2, v3
	v_xor_b32_e32 v3, 2, v232
	v_cmp_lt_i32_e32 vcc, v3, v2
	v_mov_b32_e32 v36, 0
	s_mov_b32 s15, -1
	v_cndmask_b32_e32 v3, v232, v3, vcc
	v_lshlrev_b32_e32 v98, 2, v3
	v_xor_b32_e32 v3, 4, v232
	v_cmp_lt_i32_e32 vcc, v3, v2
	v_lshlrev_b32_e32 v92, 2, v38
	v_mov_b32_e32 v37, v36
	v_cndmask_b32_e32 v3, v232, v3, vcc
	v_lshlrev_b32_e32 v99, 2, v3
	v_xor_b32_e32 v3, 8, v232
	v_cmp_lt_i32_e32 vcc, v3, v2
	v_mov_b32_e32 v38, v36
	v_mov_b32_e32 v39, v36
	v_cndmask_b32_e32 v3, v232, v3, vcc
	v_lshlrev_b32_e32 v100, 2, v3
	v_xor_b32_e32 v3, 16, v232
	v_cmp_lt_i32_e32 vcc, v3, v2
	v_mov_b32_e32 v52, v36
	v_mov_b32_e32 v53, v36
	v_cndmask_b32_e32 v3, v232, v3, vcc
	v_lshlrev_b32_e32 v101, 2, v3
	v_xor_b32_e32 v3, 32, v232
	v_cmp_lt_i32_e32 vcc, v3, v2
	v_mov_b32_e32 v54, v36
	v_mov_b32_e32 v55, v36
	v_cndmask_b32_e32 v2, v232, v3, vcc
	v_cmp_eq_u32_e32 vcc, 0, v1
	s_and_b64 s[8:9], s[0:1], vcc
	s_lshl_b64 s[0:1], s[6:7], 11
	v_lshlrev_b32_e32 v102, 2, v2
	v_lshl_or_b32 v90, v1, 3, s0
	v_mov_b32_e32 v91, s1
	s_lshl_b64 s[0:1], s[6:7], 3
	v_mov_b32_e32 v2, v0
	v_mov_b32_e32 v3, v0
	s_add_u32 s13, s0, 0x180000
	v_mov_b32_e32 v1, v0
	v_mov_b64_e32 v[66:67], v[2:3]
	v_mov_b64_e32 v[50:51], v[2:3]
	v_mov_b64_e32 v[42:43], v[2:3]
	v_mov_b64_e32 v[46:47], v[2:3]
	s_addc_u32 s14, s1, 0
	v_mov_b64_e32 v[64:65], v[0:1]
	v_mov_b64_e32 v[48:49], v[0:1]
	v_mov_b64_e32 v[40:41], v[0:1]
	v_mov_b64_e32 v[44:45], v[0:1]
	v_mov_b32_e32 v56, v36
	v_mov_b32_e32 v57, v36
	v_mov_b32_e32 v58, v36
	v_mov_b32_e32 v59, v36
	v_mov_b32_e32 v60, v36
	v_mov_b32_e32 v61, v36
	v_mov_b32_e32 v62, v36
	v_mov_b32_e32 v63, v36
	s_mov_b32 s100, s6
	s_add_i32 s101, s100, 0xffff8000
	s_cmp_lt_i32 s100, 0x8000
	s_cselect_b32 s100, s100, s101
	s_cselect_b32 s18, s74, s2
	s_cselect_b32 s19, s75, s12
	s_mov_b32 s101, 0
	s_lshl_b64 s[100:101], s[100:101], 12
	s_add_u32 s100, s18, s100
	s_addc_u32 s101, s19, s101
	global_load_dwordx4 v[106:109], v92, s[100:101]
	global_load_dwordx4 v[110:113], v92, s[100:101] offset:1024
	global_load_dwordx4 v[114:117], v92, s[100:101] offset:2048
	global_load_dwordx4 v[118:121], v92, s[100:101] offset:3072
	s_waitcnt vmcnt(0)
	s_branch .LBB0_334

.LBB0_334:
	s_cmp_lt_i32 s6, 0x8000
	s_cselect_b64 s[0:1], -1, 0
	s_and_b64 s[10:11], s[0:1], exec
	s_cselect_b32 s10, 1, 2
	s_cmpk_gt_i32 s6, 0x3fff
	s_cselect_b32 s10, s10, 0
	s_cmp_eq_u32 s10, s15
	v_readlane_b32 s38, v253, 62
	s_cselect_b64 s[18:19], -1, 0
	v_readlane_b32 s39, v253, 63
	s_or_b64 s[18:19], s[38:39], s[18:19]
	s_and_b64 vcc, exec, s[18:19]
	s_cbranch_vccnz .LBB0_336
	s_mul_i32 s92, s10, 0x9000
	v_lshl_add_u64 v[2:3], v[86:87], 0, s[92:93]
	v_lshl_add_u64 v[64:65], v[88:89], 0, s[92:93]
	global_load_dwordx4 v[36:39], v[2:3], off
	global_load_dwordx4 v[52:55], v[2:3], off offset:1024
	global_load_dwordx4 v[44:47], v[64:65], off
	global_load_dwordx4 v[40:43], v[64:65], off offset:1024
	global_load_dwordx4 v[56:59], v[2:3], off offset:2048
	global_load_dwordx4 v[60:63], v[2:3], off offset:3072
	global_load_dwordx4 v[48:51], v[64:65], off offset:2048
	s_nop 0
	global_load_dwordx4 v[64:67], v[64:65], off offset:3072
	s_mov_b32 s15, s10
	s_waitcnt vmcnt(0)
.LBB0_336:
	s_add_i32 s10, s6, 0xffff8000
	s_and_b64 s[0:1], s[0:1], exec
	s_cselect_b32 s1, s7, 0
	s_cselect_b32 s0, s6, s10
	s_cselect_b32 s11, s75, s12
	s_cselect_b32 s10, s74, s2
	s_lshl_b64 s[0:1], s[0:1], 12
	s_add_u32 s10, s10, s0
	s_addc_u32 s11, s11, s1
	s_waitcnt vmcnt(4)
	v_mov_b32_e32 v80, v106
	v_mov_b32_e32 v81, v107
	v_mov_b32_e32 v82, v108
	v_mov_b32_e32 v83, v109
	v_mov_b32_e32 v76, v110
	v_mov_b32_e32 v77, v111
	v_mov_b32_e32 v78, v112
	v_mov_b32_e32 v79, v113
	v_mov_b32_e32 v72, v114
	v_mov_b32_e32 v73, v115
	v_mov_b32_e32 v74, v116
	v_mov_b32_e32 v75, v117
	v_mov_b32_e32 v68, v118
	v_mov_b32_e32 v69, v119
	v_mov_b32_e32 v70, v120
	v_mov_b32_e32 v71, v121
	s_add_i32 s100, s6, s34
	s_cmp_ge_i32 s100, s40
	s_cbranch_scc1 .Lrpf_skip_f1
	s_add_i32 s101, s100, 0xffff8000
	s_cmp_lt_i32 s100, 0x8000
	s_cselect_b32 s100, s100, s101
	s_cselect_b32 s18, s74, s2
	s_cselect_b32 s19, s75, s12
	s_mov_b32 s101, 0
	s_lshl_b64 s[100:101], s[100:101], 12
	s_add_u32 s100, s18, s100
	s_addc_u32 s101, s19, s101
	global_load_dwordx4 v[106:109], v92, s[100:101]
	global_load_dwordx4 v[110:113], v92, s[100:101] offset:1024
	global_load_dwordx4 v[114:117], v92, s[100:101] offset:2048
	global_load_dwordx4 v[118:121], v92, s[100:101] offset:3072
.Lrpf_skip_f1:
	s_cmp_lt_i32 s6, 0x8000
	s_cbranch_scc1 .Lfxa_skip
	s_add_u32 s100, s10, 0x17700000
	s_addc_u32 s101, s11, 0
	global_load_dwordx4 v[130:133], v92, s[100:101]
	global_load_dwordx4 v[134:137], v92, s[100:101] offset:1024
	global_load_dwordx4 v[138:141], v92, s[100:101] offset:2048
	global_load_dwordx4 v[142:145], v92, s[100:101] offset:3072
	s_add_u32 s100, s100, 0x200000
	s_addc_u32 s101, s101, 0
	global_load_dwordx4 v[146:149], v92, s[100:101]
	global_load_dwordx4 v[150:153], v92, s[100:101] offset:1024
	global_load_dwordx4 v[154:157], v92, s[100:101] offset:2048
	global_load_dwordx4 v[158:161], v92, s[100:101] offset:3072
	s_add_u32 s100, s100, 0x200000
	s_addc_u32 s101, s101, 0
	global_load_dwordx4 v[162:165], v92, s[100:101]
	global_load_dwordx4 v[166:169], v92, s[100:101] offset:1024
	global_load_dwordx4 v[170:173], v92, s[100:101] offset:2048
	global_load_dwordx4 v[174:177], v92, s[100:101] offset:3072
	s_waitcnt vmcnt(0)
	v_add_f32_e32 v80, v80, v130
	v_add_f32_e32 v81, v81, v131
	v_add_f32_e32 v82, v82, v132
	v_add_f32_e32 v83, v83, v133
	v_add_f32_e32 v76, v76, v134
	v_add_f32_e32 v77, v77, v135
	v_add_f32_e32 v78, v78, v136
	v_add_f32_e32 v79, v79, v137
	v_add_f32_e32 v72, v72, v138
	v_add_f32_e32 v73, v73, v139
	v_add_f32_e32 v74, v74, v140
	v_add_f32_e32 v75, v75, v141
	v_add_f32_e32 v68, v68, v142
	v_add_f32_e32 v69, v69, v143
	v_add_f32_e32 v70, v70, v144
	v_add_f32_e32 v71, v71, v145
	v_add_f32_e32 v80, v80, v146
	v_add_f32_e32 v81, v81, v147
	v_add_f32_e32 v82, v82, v148
	v_add_f32_e32 v83, v83, v149
	v_add_f32_e32 v76, v76, v150
	v_add_f32_e32 v77, v77, v151
	v_add_f32_e32 v78, v78, v152
	v_add_f32_e32 v79, v79, v153
	v_add_f32_e32 v72, v72, v154
	v_add_f32_e32 v73, v73, v155
	v_add_f32_e32 v74, v74, v156
	v_add_f32_e32 v75, v75, v157
	v_add_f32_e32 v68, v68, v158
	v_add_f32_e32 v69, v69, v159
	v_add_f32_e32 v70, v70, v160
	v_add_f32_e32 v71, v71, v161
	v_add_f32_e32 v80, v80, v162
	v_add_f32_e32 v81, v81, v163
	v_add_f32_e32 v82, v82, v164
	v_add_f32_e32 v83, v83, v165
	v_add_f32_e32 v76, v76, v166
	v_add_f32_e32 v77, v77, v167
	v_add_f32_e32 v78, v78, v168
	v_add_f32_e32 v79, v79, v169
	v_add_f32_e32 v72, v72, v170
	v_add_f32_e32 v73, v73, v171
	v_add_f32_e32 v74, v74, v172
	v_add_f32_e32 v75, v75, v173
	v_add_f32_e32 v68, v68, v174
	v_add_f32_e32 v69, v69, v175
	v_add_f32_e32 v70, v70, v176
	v_add_f32_e32 v71, v71, v177
	global_store_dwordx4 v92, v[80:83], s[10:11]
	global_store_dwordx4 v92, v[76:79], s[10:11] offset:1024
	global_store_dwordx4 v92, v[72:75], s[10:11] offset:2048
	global_store_dwordx4 v92, v[68:71], s[10:11] offset:3072
	s_nop 1
.Lfxa_skip:
	v_mov_b32_e32 v2, v81
	v_mov_b32_e32 v3, v82
	v_mov_b32_e32 v84, v80
	v_mov_b32_e32 v85, v83
	v_pk_add_f32 v[2:3], v[2:3], v[84:85]
	v_mov_b32_e32 v84, v77
	v_mov_b32_e32 v85, v78
	v_mov_b32_e32 v94, v76
	v_mov_b32_e32 v95, v79
	v_pk_add_f32 v[84:85], v[84:85], v[94:95]
	v_add_f32_e32 v1, v2, v3
	v_pk_add_f32 v[84:85], v[84:85], v[84:85] op_sel:[0,1] op_sel_hi:[1,0]
	v_add_f32_e32 v2, 0, v1
	v_add_f32_e32 v94, v72, v73
	v_add_f32_e32 v104, v74, v75
	v_mov_b32_e32 v3, v68
	v_mov_b32_e32 v85, v69
	v_mov_b32_e32 v95, v70
	v_mov_b32_e32 v105, v71
	v_pk_add_f32 v[2:3], v[2:3], v[84:85]
	v_pk_add_f32 v[84:85], v[94:95], v[104:105]
	s_nop 0
	v_pk_add_f32 v[2:3], v[2:3], v[84:85]
	s_nop 0
	v_add_f32_e32 v1, v2, v3
	s_nop 1
	v_add_f32_dpp v1, v1, v1 quad_perm:[1,0,3,2] row_mask:0xf bank_mask:0xf
	s_nop 1
	v_add_f32_dpp v1, v1, v1 quad_perm:[2,3,0,1] row_mask:0xf bank_mask:0xf
	s_nop 1
	v_add_f32_dpp v1, v1, v1 row_half_mirror row_mask:0xf bank_mask:0xf
	s_nop 1
	v_add_f32_dpp v1, v1, v1 row_mirror row_mask:0xf bank_mask:0xf
	v_mov_b32_e32 v2, v1
	s_nop 1
	v_permlane16_swap_b32_e32 v1, v2
	v_add_f32_e32 v1, v1, v2
	v_mov_b32_e32 v2, v1
	s_nop 1
	v_permlane32_swap_b32_e32 v1, v2
	v_add_f32_e32 v1, v1, v2
	v_fmamk_f32 v3, v1, 0xba800000, v83
	v_fmamk_f32 v81, v1, 0xba800000, v81
	v_fmamk_f32 v2, v1, 0xba800000, v82
	v_fmac_f32_e32 v80, 0xba800000, v1
	v_mul_f32_e32 v82, v81, v81
	v_mul_f32_e32 v83, v3, v3
	v_fmac_f32_e32 v82, v80, v80
	v_fmac_f32_e32 v83, v2, v2
	v_add_f32_e32 v84, v82, v83
	v_fmamk_f32 v83, v1, 0xba800000, v79
	v_fmamk_f32 v77, v1, 0xba800000, v77
	v_fmamk_f32 v82, v1, 0xba800000, v78
	v_fmac_f32_e32 v76, 0xba800000, v1
	v_mul_f32_e32 v78, v77, v77
	v_mul_f32_e32 v79, v83, v83
	v_fmac_f32_e32 v78, v76, v76
	v_fmac_f32_e32 v79, v82, v82
	v_add_f32_e32 v78, v78, v79
	v_fmamk_f32 v85, v1, 0xba800000, v75
	v_fmamk_f32 v73, v1, 0xba800000, v73
	v_add_f32_e32 v78, v84, v78
	v_fmamk_f32 v84, v1, 0xba800000, v74
	v_fmac_f32_e32 v72, 0xba800000, v1
	v_mul_f32_e32 v74, v73, v73
	v_mul_f32_e32 v75, v85, v85
	v_fmamk_f32 v95, v1, 0xba800000, v71
	v_fmamk_f32 v69, v1, 0xba800000, v69
	v_fmac_f32_e32 v74, v72, v72
	v_fmac_f32_e32 v75, v84, v84
	v_fmamk_f32 v94, v1, 0xba800000, v70
	v_fmac_f32_e32 v68, 0xba800000, v1
	v_mul_f32_e32 v70, v69, v69
	v_mul_f32_e32 v71, v95, v95
	v_add_f32_e32 v74, v74, v75
	v_fmac_f32_e32 v70, v68, v68
	v_fmac_f32_e32 v71, v94, v94
	v_add_f32_e32 v74, v74, v78
	v_add_f32_e32 v70, v70, v71
	v_add_f32_e32 v70, v70, v74
	s_nop 1
	v_add_f32_dpp v70, v70, v70 quad_perm:[1,0,3,2] row_mask:0xf bank_mask:0xf
	s_nop 1
	v_add_f32_dpp v70, v70, v70 quad_perm:[2,3,0,1] row_mask:0xf bank_mask:0xf
	s_nop 1
	v_add_f32_dpp v70, v70, v70 row_half_mirror row_mask:0xf bank_mask:0xf
	s_nop 1
	v_add_f32_dpp v70, v70, v70 row_mirror row_mask:0xf bank_mask:0xf
	v_mov_b32_e32 v71, v70
	s_nop 1
	v_permlane16_swap_b32_e32 v70, v71
	v_add_f32_e32 v70, v70, v71
	v_mov_b32_e32 v71, v70
	s_nop 1
	v_permlane32_swap_b32_e32 v70, v71
	v_add_f32_e32 v70, v70, v71
	v_fmamk_f32 v70, v70, 0x3a800000, v228
	v_cmp_gt_f32_e32 vcc, s49, v70
	v_mul_f32_e32 v71, 0x4f800000, v70
	s_nop 0
	v_cndmask_b32_e32 v70, v70, v71, vcc
	v_sqrt_f32_e32 v71, v70
	s_nop 0
	v_add_u32_e32 v74, -1, v71
	v_fma_f32 v75, -v74, v71, v70
	v_cmp_ge_f32_e64 s[0:1], 0, v75
	v_add_u32_e32 v75, 1, v71
	s_nop 0
	v_cndmask_b32_e64 v74, v71, v74, s[0:1]
	v_fma_f32 v71, -v75, v71, v70
	v_cmp_lt_f32_e64 s[0:1], 0, v71
	s_nop 1
	v_cndmask_b32_e64 v71, v74, v75, s[0:1]
	v_mul_f32_e32 v74, 0x37800000, v71
	v_cndmask_b32_e32 v71, v71, v74, vcc
	v_cmp_class_f32_e32 vcc, v70, v229
	s_nop 1
	v_cndmask_b32_e32 v70, v71, v70, vcc
	v_div_scale_f32 v71, s[0:1], v70, v70, 1.0
	v_rcp_f32_e32 v74, v71
	s_nop 0
	v_fma_f32 v75, -v71, v74, 1.0
	v_fmac_f32_e32 v74, v75, v74
	v_div_scale_f32 v75, vcc, 1.0, v70, 1.0
	v_mul_f32_e32 v78, v75, v74
	v_fma_f32 v79, -v71, v78, v75
	v_fmac_f32_e32 v78, v79, v74
	v_fma_f32 v71, -v71, v78, v75
	v_div_fmas_f32 v71, v71, v74, v78
	v_div_fixup_f32 v96, v71, v70, 1.0
	s_and_saveexec_b64 s[0:1], s[8:9]
	s_cbranch_execz .LBB0_338
	s_add_u32 s18, s4, s13
	v_mul_f32_e32 v70, 0x3a800000, v1
	s_addc_u32 s19, s5, s14
	v_mov_b32_e32 v71, v96
	global_store_dwordx2 v0, v[70:71], s[18:19]

.LBB0_397:
	s_and_b64 vcc, exec, s[0:1]
	s_cbranch_vccz .LBB0_908
	v_mov_b32_e32 v1, v222
	v_readlane_b32 s64, v253, 60
	v_readfirstlane_b32 s0, v1
	s_ashr_i32 s0, s0, 6
	s_add_i32 s8, s0, s90
	s_mov_b64 s[6:7], s[56:57]
	s_cmp_gt_i32 s8, 0x81ff
	s_movk_i32 s59, 0x1400
	s_mov_b32 s60, 0x3e8293ee
	v_readlane_b32 s61, v254, 51
	v_readlane_b32 s62, v254, 52
	v_readlane_b32 s65, v253, 61
	v_readlane_b32 s63, v254, 47
	v_readlane_b32 s66, v254, 48
	s_cbranch_scc1 .LBB0_405
	v_and_b32_e32 v1, 63, v1
	v_readlane_b32 s0, v254, 11
	v_readlane_b32 s2, v254, 15
	v_lshlrev_b32_e32 v2, 4, v1
	v_readlane_b32 s1, v254, 12
	v_readlane_b32 s3, v254, 16
	s_nop 3
	global_load_dwordx4 v[4:7], v2, s[0:1]
	global_load_dwordx4 v[8:11], v2, s[0:1] offset:1024
	global_load_dwordx4 v[12:15], v2, s[2:3]
	global_load_dwordx4 v[16:19], v2, s[2:3] offset:1024
	global_load_dwordx4 v[20:23], v2, s[0:1] offset:2048
	global_load_dwordx4 v[24:27], v2, s[0:1] offset:3072
	global_load_dwordx4 v[28:31], v2, s[2:3] offset:2048
	global_load_dwordx4 v[32:35], v2, s[2:3] offset:3072
	v_readlane_b32 s0, v254, 25
	v_mov_b32_e32 v3, v0
	v_readlane_b32 s1, v254, 26
	s_add_u32 s2, s6, 0x200000
	s_addc_u32 s10, s7, 0
	v_lshl_add_u64 v[84:85], s[0:1], 0, v[2:3]
	v_readlane_b32 s0, v254, 23
	v_readlane_b32 s1, v254, 24
	s_ashr_i32 s9, s8, 31
	s_lshl_b64 s[4:5], s[8:9], 11
	v_lshl_add_u64 v[86:87], s[0:1], 0, v[2:3]
	v_and_b32_e32 v2, 64, v232
	v_add_u32_e32 v2, 64, v2
	v_xor_b32_e32 v3, 1, v232
	v_cmp_lt_i32_e32 vcc, v3, v2
	v_lshl_or_b32 v88, v1, 3, s4
	v_mov_b32_e32 v89, s5
	v_cndmask_b32_e32 v3, v232, v3, vcc
	v_lshlrev_b32_e32 v90, 2, v3
	v_xor_b32_e32 v3, 2, v232
	v_cmp_lt_i32_e32 vcc, v3, v2
	s_lshl_b64 s[4:5], s[8:9], 3
	v_lshlrev_b32_e32 v38, 2, v1
	v_cndmask_b32_e32 v3, v232, v3, vcc
	v_lshlrev_b32_e32 v91, 2, v3
	v_xor_b32_e32 v3, 4, v232
	v_cmp_lt_i32_e32 vcc, v3, v2
	v_cmp_eq_u32_e64 s[0:1], 0, v1
	s_add_u32 s11, s4, 0x180000
	v_cndmask_b32_e32 v3, v232, v3, vcc
	v_lshlrev_b32_e32 v92, 2, v3
	v_xor_b32_e32 v3, 8, v232
	v_cmp_lt_i32_e32 vcc, v3, v2
	v_mov_b32_e32 v1, v0
	v_mov_b32_e32 v36, 0
	v_cndmask_b32_e32 v3, v232, v3, vcc
	v_lshlrev_b32_e32 v93, 2, v3
	v_xor_b32_e32 v3, 16, v232
	v_cmp_lt_i32_e32 vcc, v3, v2
	s_mov_b32 s13, -1
	s_addc_u32 s12, s5, 0
	v_cndmask_b32_e32 v3, v232, v3, vcc
	v_lshlrev_b32_e32 v94, 2, v3
	v_xor_b32_e32 v3, 32, v232
	v_cmp_lt_i32_e32 vcc, v3, v2
	v_lshlrev_b32_e32 v96, 2, v38
	v_mov_b32_e32 v37, v36
	v_cndmask_b32_e32 v2, v232, v3, vcc
	v_lshlrev_b32_e32 v95, 2, v2
	v_mov_b32_e32 v2, v0
	v_mov_b32_e32 v3, v0
	v_mov_b64_e32 v[66:67], v[2:3]
	v_mov_b64_e32 v[50:51], v[2:3]
	v_mov_b64_e32 v[42:43], v[2:3]
	v_mov_b64_e32 v[46:47], v[2:3]
	v_mov_b64_e32 v[64:65], v[0:1]
	v_mov_b64_e32 v[48:49], v[0:1]
	v_mov_b64_e32 v[40:41], v[0:1]
	v_mov_b64_e32 v[44:45], v[0:1]
	v_mov_b32_e32 v38, v36
	v_mov_b32_e32 v39, v36
	v_mov_b32_e32 v52, v36
	v_mov_b32_e32 v53, v36
	v_mov_b32_e32 v54, v36
	v_mov_b32_e32 v55, v36
	v_mov_b32_e32 v56, v36
	v_mov_b32_e32 v57, v36
	v_mov_b32_e32 v58, v36
	v_mov_b32_e32 v59, v36
	v_mov_b32_e32 v60, v36
	v_mov_b32_e32 v61, v36
	v_mov_b32_e32 v62, v36
	v_mov_b32_e32 v63, v36
	s_mov_b32 s100, s8
	s_add_i32 s101, s100, 0xffff8000
	s_cmp_lt_i32 s100, 0x8000
	s_cselect_b32 s100, s100, s101
	s_cselect_b32 s15, s74, s2
	s_cselect_b32 s14, s75, s10
	s_mov_b32 s101, 0
	s_lshl_b64 s[100:101], s[100:101], 12
	s_add_u32 s100, s15, s100
	s_addc_u32 s101, s14, s101
	global_load_dwordx4 v[106:109], v96, s[100:101]
	global_load_dwordx4 v[110:113], v96, s[100:101] offset:1024
	global_load_dwordx4 v[114:117], v96, s[100:101] offset:2048
	global_load_dwordx4 v[118:121], v96, s[100:101] offset:3072
	s_waitcnt vmcnt(0)
	s_branch .LBB0_401

.LBB0_401:
	s_cmp_lt_i32 s8, 0x8000
	s_cselect_b64 s[4:5], -1, 0
	s_and_b64 s[14:15], s[4:5], exec
	s_cselect_b32 s14, 1, 2
	s_cmpk_gt_i32 s8, 0x3fff
	s_cselect_b32 s14, s14, 0
	s_cmp_eq_u32 s14, s13
	s_cbranch_scc1 .LBB0_403
	s_mul_i32 s92, s14, 0x9000
	v_lshl_add_u64 v[2:3], v[84:85], 0, s[92:93]
	v_lshl_add_u64 v[64:65], v[86:87], 0, s[92:93]
	global_load_dwordx4 v[36:39], v[2:3], off
	global_load_dwordx4 v[52:55], v[2:3], off offset:1024
	global_load_dwordx4 v[44:47], v[64:65], off
	global_load_dwordx4 v[40:43], v[64:65], off offset:1024
	global_load_dwordx4 v[56:59], v[2:3], off offset:2048
	global_load_dwordx4 v[60:63], v[2:3], off offset:3072
	global_load_dwordx4 v[48:51], v[64:65], off offset:2048
	s_nop 0
	global_load_dwordx4 v[64:67], v[64:65], off offset:3072
	s_mov_b32 s13, s14
	s_waitcnt vmcnt(0)
.LBB0_403:
	s_add_i32 s14, s8, 0xffff8000
	s_and_b64 s[4:5], s[4:5], exec
	s_cselect_b32 s5, s9, 0
	s_cselect_b32 s4, s8, s14
	s_cselect_b32 s14, s75, s10
	s_cselect_b32 s15, s74, s2
	s_lshl_b64 s[4:5], s[4:5], 12
	s_add_u32 s4, s15, s4
	s_addc_u32 s5, s14, s5
	s_waitcnt vmcnt(4)
	v_mov_b32_e32 v80, v106
	v_mov_b32_e32 v81, v107
	v_mov_b32_e32 v82, v108
	v_mov_b32_e32 v83, v109
	v_mov_b32_e32 v76, v110
	v_mov_b32_e32 v77, v111
	v_mov_b32_e32 v78, v112
	v_mov_b32_e32 v79, v113
	v_mov_b32_e32 v72, v114
	v_mov_b32_e32 v73, v115
	v_mov_b32_e32 v74, v116
	v_mov_b32_e32 v75, v117
	v_mov_b32_e32 v68, v118
	v_mov_b32_e32 v69, v119
	v_mov_b32_e32 v70, v120
	v_mov_b32_e32 v71, v121
	s_add_i32 s100, s8, s34
	s_cmp_ge_i32 s100, 0x8200
	s_cbranch_scc1 .Lrpf_skip_f0
	s_add_i32 s101, s100, 0xffff8000
	s_cmp_lt_i32 s100, 0x8000
	s_cselect_b32 s100, s100, s101
	s_cselect_b32 s15, s74, s2
	s_cselect_b32 s14, s75, s10
	s_mov_b32 s101, 0
	s_lshl_b64 s[100:101], s[100:101], 12
	s_add_u32 s100, s15, s100
	s_addc_u32 s101, s14, s101
	global_load_dwordx4 v[106:109], v96, s[100:101]
	global_load_dwordx4 v[110:113], v96, s[100:101] offset:1024
	global_load_dwordx4 v[114:117], v96, s[100:101] offset:2048
	global_load_dwordx4 v[118:121], v96, s[100:101] offset:3072
.Lrpf_skip_f0:
	s_cmp_lt_i32 s8, 0x8000
	s_cbranch_scc1 .Lfxb_skip
	s_add_u32 s100, s4, 0x17700000
	s_addc_u32 s101, s5, 0
	global_load_dwordx4 v[130:133], v96, s[100:101]
	global_load_dwordx4 v[134:137], v96, s[100:101] offset:1024
	global_load_dwordx4 v[138:141], v96, s[100:101] offset:2048
	global_load_dwordx4 v[142:145], v96, s[100:101] offset:3072
	s_add_u32 s100, s100, 0x200000
	s_addc_u32 s101, s101, 0
	global_load_dwordx4 v[146:149], v96, s[100:101]
	global_load_dwordx4 v[150:153], v96, s[100:101] offset:1024
	global_load_dwordx4 v[154:157], v96, s[100:101] offset:2048
	global_load_dwordx4 v[158:161], v96, s[100:101] offset:3072
	s_add_u32 s100, s100, 0x200000
	s_addc_u32 s101, s101, 0
	global_load_dwordx4 v[162:165], v96, s[100:101]
	global_load_dwordx4 v[166:169], v96, s[100:101] offset:1024
	global_load_dwordx4 v[170:173], v96, s[100:101] offset:2048
	global_load_dwordx4 v[174:177], v96, s[100:101] offset:3072
	s_waitcnt vmcnt(0)
	v_add_f32_e32 v80, v80, v130
	v_add_f32_e32 v81, v81, v131
	v_add_f32_e32 v82, v82, v132
	v_add_f32_e32 v83, v83, v133
	v_add_f32_e32 v76, v76, v134
	v_add_f32_e32 v77, v77, v135
	v_add_f32_e32 v78, v78, v136
	v_add_f32_e32 v79, v79, v137
	v_add_f32_e32 v72, v72, v138
	v_add_f32_e32 v73, v73, v139
	v_add_f32_e32 v74, v74, v140
	v_add_f32_e32 v75, v75, v141
	v_add_f32_e32 v68, v68, v142
	v_add_f32_e32 v69, v69, v143
	v_add_f32_e32 v70, v70, v144
	v_add_f32_e32 v71, v71, v145
	v_add_f32_e32 v80, v80, v146
	v_add_f32_e32 v81, v81, v147
	v_add_f32_e32 v82, v82, v148
	v_add_f32_e32 v83, v83, v149
	v_add_f32_e32 v76, v76, v150
	v_add_f32_e32 v77, v77, v151
	v_add_f32_e32 v78, v78, v152
	v_add_f32_e32 v79, v79, v153
	v_add_f32_e32 v72, v72, v154
	v_add_f32_e32 v73, v73, v155
	v_add_f32_e32 v74, v74, v156
	v_add_f32_e32 v75, v75, v157
	v_add_f32_e32 v68, v68, v158
	v_add_f32_e32 v69, v69, v159
	v_add_f32_e32 v70, v70, v160
	v_add_f32_e32 v71, v71, v161
	v_add_f32_e32 v80, v80, v162
	v_add_f32_e32 v81, v81, v163
	v_add_f32_e32 v82, v82, v164
	v_add_f32_e32 v83, v83, v165
	v_add_f32_e32 v76, v76, v166
	v_add_f32_e32 v77, v77, v167
	v_add_f32_e32 v78, v78, v168
	v_add_f32_e32 v79, v79, v169
	v_add_f32_e32 v72, v72, v170
	v_add_f32_e32 v73, v73, v171
	v_add_f32_e32 v74, v74, v172
	v_add_f32_e32 v75, v75, v173
	v_add_f32_e32 v68, v68, v174
	v_add_f32_e32 v69, v69, v175
	v_add_f32_e32 v70, v70, v176
	v_add_f32_e32 v71, v71, v177
	global_store_dwordx4 v96, v[80:83], s[4:5]
	global_store_dwordx4 v96, v[76:79], s[4:5] offset:1024
	global_store_dwordx4 v96, v[72:75], s[4:5] offset:2048
	global_store_dwordx4 v96, v[68:71], s[4:5] offset:3072
	s_nop 1
.Lfxb_skip:
	v_mov_b32_e32 v2, v81
	v_mov_b32_e32 v3, v82
	v_mov_b32_e32 v98, v80
	v_mov_b32_e32 v99, v83
	v_pk_add_f32 v[2:3], v[2:3], v[98:99]
	v_mov_b32_e32 v98, v77
	v_mov_b32_e32 v99, v78
	v_mov_b32_e32 v100, v76
	v_mov_b32_e32 v101, v79
	v_pk_add_f32 v[98:99], v[98:99], v[100:101]
	v_add_f32_e32 v1, v2, v3
	v_pk_add_f32 v[98:99], v[98:99], v[98:99] op_sel:[0,1] op_sel_hi:[1,0]
	v_add_f32_e32 v2, 0, v1
	v_add_f32_e32 v100, v72, v73
	v_add_f32_e32 v102, v74, v75
	v_mov_b32_e32 v3, v68
	v_mov_b32_e32 v99, v69
	v_mov_b32_e32 v101, v70
	v_mov_b32_e32 v103, v71
	v_pk_add_f32 v[2:3], v[2:3], v[98:99]
	v_pk_add_f32 v[98:99], v[100:101], v[102:103]
	s_nop 0
	v_pk_add_f32 v[2:3], v[2:3], v[98:99]
	s_nop 0
	v_add_f32_e32 v1, v2, v3
	s_nop 1
	v_add_f32_dpp v1, v1, v1 quad_perm:[1,0,3,2] row_mask:0xf bank_mask:0xf
	s_nop 1
	v_add_f32_dpp v1, v1, v1 quad_perm:[2,3,0,1] row_mask:0xf bank_mask:0xf
	s_nop 1
	v_add_f32_dpp v1, v1, v1 row_half_mirror row_mask:0xf bank_mask:0xf
	s_nop 1
	v_add_f32_dpp v1, v1, v1 row_mirror row_mask:0xf bank_mask:0xf
	v_mov_b32_e32 v2, v1
	s_nop 1
	v_permlane16_swap_b32_e32 v1, v2
	v_add_f32_e32 v1, v1, v2
	v_mov_b32_e32 v2, v1
	s_nop 1
	v_permlane32_swap_b32_e32 v1, v2
	v_add_f32_e32 v1, v1, v2
	v_fmamk_f32 v3, v1, 0xba800000, v83
	v_fmamk_f32 v81, v1, 0xba800000, v81
	v_fmamk_f32 v2, v1, 0xba800000, v82
	v_fmac_f32_e32 v80, 0xba800000, v1
	v_mul_f32_e32 v82, v81, v81
	v_mul_f32_e32 v83, v3, v3
	v_fmac_f32_e32 v82, v80, v80
	v_fmac_f32_e32 v83, v2, v2
	v_fmamk_f32 v79, v1, 0xba800000, v79
	v_fmamk_f32 v77, v1, 0xba800000, v77
	v_add_f32_e32 v82, v82, v83
	v_fmamk_f32 v78, v1, 0xba800000, v78
	v_fmac_f32_e32 v76, 0xba800000, v1
	v_mul_f32_e32 v83, v77, v77
	v_mul_f32_e32 v97, v79, v79
	v_fmac_f32_e32 v83, v76, v76
	v_fmac_f32_e32 v97, v78, v78
	v_add_f32_e32 v83, v83, v97
	v_fmamk_f32 v75, v1, 0xba800000, v75
	v_fmamk_f32 v73, v1, 0xba800000, v73
	v_add_f32_e32 v82, v82, v83
	v_fmamk_f32 v74, v1, 0xba800000, v74
	v_fmac_f32_e32 v72, 0xba800000, v1
	v_mul_f32_e32 v83, v73, v73
	v_mul_f32_e32 v97, v75, v75
	v_fmac_f32_e32 v83, v72, v72
	v_fmac_f32_e32 v97, v74, v74
	v_add_f32_e32 v83, v83, v97
	v_fmamk_f32 v71, v1, 0xba800000, v71
	v_fmamk_f32 v69, v1, 0xba800000, v69
	v_add_f32_e32 v82, v83, v82
	v_fmamk_f32 v70, v1, 0xba800000, v70
	v_fmac_f32_e32 v68, 0xba800000, v1
	v_mul_f32_e32 v83, v69, v69
	v_mul_f32_e32 v97, v71, v71
	v_fmac_f32_e32 v83, v68, v68
	v_fmac_f32_e32 v97, v70, v70
	v_add_f32_e32 v83, v83, v97
	v_add_f32_e32 v82, v83, v82
	s_nop 1
	v_add_f32_dpp v82, v82, v82 quad_perm:[1,0,3,2] row_mask:0xf bank_mask:0xf
	s_nop 1
	v_add_f32_dpp v82, v82, v82 quad_perm:[2,3,0,1] row_mask:0xf bank_mask:0xf
	s_nop 1
	v_add_f32_dpp v82, v82, v82 row_half_mirror row_mask:0xf bank_mask:0xf
	s_nop 1
	v_add_f32_dpp v82, v82, v82 row_mirror row_mask:0xf bank_mask:0xf
	v_mov_b32_e32 v83, v82
	s_nop 1
	v_permlane16_swap_b32_e32 v82, v83
	v_add_f32_e32 v82, v82, v83
	v_mov_b32_e32 v83, v82
	s_nop 1
	v_permlane32_swap_b32_e32 v82, v83
	v_add_f32_e32 v82, v82, v83
	v_fmamk_f32 v82, v82, 0x3a800000, v228
	v_cmp_gt_f32_e32 vcc, s49, v82
	v_mul_f32_e32 v83, 0x4f800000, v82
	s_nop 0
	v_cndmask_b32_e32 v82, v82, v83, vcc
	v_sqrt_f32_e32 v83, v82
	s_nop 0
	v_add_u32_e32 v97, -1, v83
	v_fma_f32 v98, -v97, v83, v82
	v_cmp_ge_f32_e64 s[4:5], 0, v98
	v_add_u32_e32 v98, 1, v83
	s_nop 0
	v_cndmask_b32_e64 v97, v83, v97, s[4:5]
	v_fma_f32 v83, -v98, v83, v82
	v_cmp_lt_f32_e64 s[4:5], 0, v83
	s_nop 1
	v_cndmask_b32_e64 v83, v97, v98, s[4:5]
	v_mul_f32_e32 v97, 0x37800000, v83
	v_cndmask_b32_e32 v83, v83, v97, vcc
	v_cmp_class_f32_e32 vcc, v82, v229
	s_nop 1
	v_cndmask_b32_e32 v82, v83, v82, vcc
	v_div_scale_f32 v83, s[4:5], v82, v82, 1.0
	v_rcp_f32_e32 v97, v83
	s_nop 0
	v_fma_f32 v98, -v83, v97, 1.0
	v_fmac_f32_e32 v97, v98, v97
	v_div_scale_f32 v98, vcc, 1.0, v82, 1.0
	v_mul_f32_e32 v99, v98, v97
	v_fma_f32 v100, -v83, v99, v98
	v_fmac_f32_e32 v99, v100, v97
	v_fma_f32 v83, -v83, v99, v98
	v_div_fmas_f32 v83, v83, v97, v99
	v_div_fixup_f32 v82, v83, v82, 1.0
	s_and_saveexec_b64 s[4:5], s[0:1]
	s_cbranch_execz .LBB0_400
	s_add_u32 s14, s6, s11
	v_mul_f32_e32 v98, 0x3a800000, v1
	s_addc_u32 s15, s7, s12
	v_mov_b32_e32 v99, v82
	global_store_dwordx2 v0, v[98:99], s[14:15]
	s_branch .LBB0_400

.LBB0_848:
	s_or_b64 exec, exec, s[0:1]
	v_mov_b32_e32 v1, v222
	s_waitcnt lgkmcnt(0)
	s_barrier
	s_mov_b64 s[6:7], s[56:57]
	v_readfirstlane_b32 s0, v1
	s_ashr_i32 s0, s0, 6
	s_add_i32 s8, s0, s90
	s_cmp_ge_i32 s8, s40
	s_cbranch_scc1 .LBB0_855
	v_and_b32_e32 v1, 63, v1
	v_readlane_b32 s0, v254, 3
	v_readlane_b32 s2, v254, 7
	v_lshlrev_b32_e32 v2, 4, v1
	v_readlane_b32 s1, v254, 4
	v_readlane_b32 s3, v254, 8
	s_nop 3
	global_load_dwordx4 v[4:7], v2, s[0:1]
	global_load_dwordx4 v[8:11], v2, s[0:1] offset:1024
	global_load_dwordx4 v[12:15], v2, s[2:3]
	global_load_dwordx4 v[16:19], v2, s[2:3] offset:1024
	global_load_dwordx4 v[20:23], v2, s[0:1] offset:2048
	global_load_dwordx4 v[24:27], v2, s[0:1] offset:3072
	global_load_dwordx4 v[28:31], v2, s[2:3] offset:2048
	global_load_dwordx4 v[32:35], v2, s[2:3] offset:3072
	v_readlane_b32 s0, v254, 43
	v_mov_b32_e32 v3, v0
	v_readlane_b32 s1, v254, 44
	s_add_u32 s2, s6, 0x200000
	s_addc_u32 s10, s7, 0
	v_lshl_add_u64 v[84:85], s[0:1], 0, v[2:3]
	v_readlane_b32 s0, v254, 39
	v_readlane_b32 s1, v254, 40
	s_ashr_i32 s9, s8, 31
	s_lshl_b64 s[4:5], s[8:9], 11
	v_lshl_add_u64 v[86:87], s[0:1], 0, v[2:3]
	v_and_b32_e32 v2, 64, v232
	v_add_u32_e32 v2, 64, v2
	v_xor_b32_e32 v3, 1, v232
	v_cmp_lt_i32_e32 vcc, v3, v2
	v_lshl_or_b32 v88, v1, 3, s4
	v_mov_b32_e32 v89, s5
	v_cndmask_b32_e32 v3, v232, v3, vcc
	v_lshlrev_b32_e32 v90, 2, v3
	v_xor_b32_e32 v3, 2, v232
	v_cmp_lt_i32_e32 vcc, v3, v2
	s_lshl_b64 s[4:5], s[8:9], 3
	v_lshlrev_b32_e32 v38, 2, v1
	v_cndmask_b32_e32 v3, v232, v3, vcc
	v_lshlrev_b32_e32 v91, 2, v3
	v_xor_b32_e32 v3, 4, v232
	v_cmp_lt_i32_e32 vcc, v3, v2
	v_cmp_eq_u32_e64 s[0:1], 0, v1
	s_add_u32 s11, s4, 0x180000
	v_cndmask_b32_e32 v3, v232, v3, vcc
	v_lshlrev_b32_e32 v92, 2, v3
	v_xor_b32_e32 v3, 8, v232
	v_cmp_lt_i32_e32 vcc, v3, v2
	v_mov_b32_e32 v1, v0
	v_mov_b32_e32 v36, 0
	v_cndmask_b32_e32 v3, v232, v3, vcc
	v_lshlrev_b32_e32 v93, 2, v3
	v_xor_b32_e32 v3, 16, v232
	v_cmp_lt_i32_e32 vcc, v3, v2
	s_mov_b32 s13, -1
	s_addc_u32 s12, s5, 0
	v_cndmask_b32_e32 v3, v232, v3, vcc
	v_lshlrev_b32_e32 v94, 2, v3
	v_xor_b32_e32 v3, 32, v232
	v_cmp_lt_i32_e32 vcc, v3, v2
	v_lshlrev_b32_e32 v96, 2, v38
	v_mov_b32_e32 v37, v36
	v_cndmask_b32_e32 v2, v232, v3, vcc
	v_lshlrev_b32_e32 v95, 2, v2
	v_mov_b32_e32 v2, v0
	v_mov_b32_e32 v3, v0
	v_mov_b64_e32 v[66:67], v[2:3]
	v_mov_b64_e32 v[50:51], v[2:3]
	v_mov_b64_e32 v[42:43], v[2:3]
	v_mov_b64_e32 v[46:47], v[2:3]
	v_mov_b64_e32 v[64:65], v[0:1]
	v_mov_b64_e32 v[48:49], v[0:1]
	v_mov_b64_e32 v[40:41], v[0:1]
	v_mov_b64_e32 v[44:45], v[0:1]
	v_mov_b32_e32 v38, v36
	v_mov_b32_e32 v39, v36
	v_mov_b32_e32 v52, v36
	v_mov_b32_e32 v53, v36
	v_mov_b32_e32 v54, v36
	v_mov_b32_e32 v55, v36
	v_mov_b32_e32 v56, v36
	v_mov_b32_e32 v57, v36
	v_mov_b32_e32 v58, v36
	v_mov_b32_e32 v59, v36
	v_mov_b32_e32 v60, v36
	v_mov_b32_e32 v61, v36
	v_mov_b32_e32 v62, v36
	v_mov_b32_e32 v63, v36
	s_mov_b32 s100, s8
	s_add_i32 s101, s100, 0xffff8000
	s_cmp_lt_i32 s100, 0x8000
	s_cselect_b32 s100, s100, s101
	s_cselect_b32 s15, s74, s2
	s_cselect_b32 s14, s75, s10
	s_mov_b32 s101, 0
	s_lshl_b64 s[100:101], s[100:101], 12
	s_add_u32 s100, s15, s100
	s_addc_u32 s101, s14, s101
	global_load_dwordx4 v[106:109], v96, s[100:101]
	global_load_dwordx4 v[110:113], v96, s[100:101] offset:1024
	global_load_dwordx4 v[114:117], v96, s[100:101] offset:2048
	global_load_dwordx4 v[118:121], v96, s[100:101] offset:3072
	s_waitcnt vmcnt(0)
	s_branch .LBB0_851

.LBB0_853:
	s_add_i32 s14, s8, 0xffff8000
	s_and_b64 s[4:5], s[4:5], exec
	s_cselect_b32 s5, s9, 0
	s_cselect_b32 s4, s8, s14
	s_cselect_b32 s14, s75, s10
	s_cselect_b32 s15, s74, s2
	s_lshl_b64 s[4:5], s[4:5], 12
	s_add_u32 s4, s15, s4
	s_addc_u32 s5, s14, s5
	s_waitcnt vmcnt(4)
	v_mov_b32_e32 v80, v106
	v_mov_b32_e32 v81, v107
	v_mov_b32_e32 v82, v108
	v_mov_b32_e32 v83, v109
	v_mov_b32_e32 v76, v110
	v_mov_b32_e32 v77, v111
	v_mov_b32_e32 v78, v112
	v_mov_b32_e32 v79, v113
	v_mov_b32_e32 v72, v114
	v_mov_b32_e32 v73, v115
	v_mov_b32_e32 v74, v116
	v_mov_b32_e32 v75, v117
	v_mov_b32_e32 v68, v118
	v_mov_b32_e32 v69, v119
	v_mov_b32_e32 v70, v120
	v_mov_b32_e32 v71, v121
	s_add_i32 s100, s8, s34
	s_cmp_ge_i32 s100, s40
	s_cbranch_scc1 .Lrpf_skip_wo
	s_add_i32 s101, s100, 0xffff8000
	s_cmp_lt_i32 s100, 0x8000
	s_cselect_b32 s100, s100, s101
	s_cselect_b32 s15, s74, s2
	s_cselect_b32 s14, s75, s10
	s_mov_b32 s101, 0
	s_lshl_b64 s[100:101], s[100:101], 12
	s_add_u32 s100, s15, s100
	s_addc_u32 s101, s14, s101
	global_load_dwordx4 v[106:109], v96, s[100:101]
	global_load_dwordx4 v[110:113], v96, s[100:101] offset:1024
	global_load_dwordx4 v[114:117], v96, s[100:101] offset:2048
	global_load_dwordx4 v[118:121], v96, s[100:101] offset:3072
